# plus prep_phase and final RMSNorm streaming loops: two rows per trip with both rows' loads in flight
# speedup vs baseline: 1.0047x; 1.0047x over previous
; DEVI int otid() { int t = threadIdx.x; asm volatile("" : "+v"(t)); return t; }
; DEVI int obid() { int t = blockIdx.x; asm volatile("" : "+s"(t)); return t; }
; DEVI u32x2 pk4(f32x4 v) { u32x2 r; r.x = cvt_pk(v[0], v[1]); r.y = cvt_pk(v[2], v[3]); return r; }
; DEVI void prep_phase(const float* src, u16* dst, float* ssq) {
;     const int lane = otid() & 63, gw = obid() * 8 + (otid() >> 6), nw = gridDim.x * 8;
;     for (int r = gw; r < T_TOK; r += nw) {
;         const float* s = src + (size_t)r * DM; f32x4 v[4]; float ss = 0.f;
; #pragma unroll
;         for (int i = 0; i < 4; ++i) { v[i] = *(const f32x4*)(s + i * 256 + lane * 4); ss += v[i][0] * v[i][0] + v[i][1] * v[i][1] + v[i][2] * v[i][2] + v[i][3] * v[i][3]; }
; #pragma unroll
;         for (int o = 32; o > 0; o >>= 1) ss += __shfl_xor(ss, o);
; #pragma unroll
;         for (int i = 0; i < 4; ++i) *(u32x2*)(dst + (size_t)r * DM + i * 256 + lane * 4) = pk4(v[i]);
;         if (lane == 0) *(f32x4*)(ssq + (size_t)r * 4) = (f32x4){ss, 0.f, 0.f, 0.f};
;     }
; }
.LBB0_203:
	s_or_b64 exec, exec, s[0:1]
	v_readlane_b32 s0, v252, 30
	v_readlane_b32 s1, v252, 31
	v_lshl_add_u64 v[4:5], v[4:5], 0, s[8:9]
	v_lshl_add_u64 v[4:5], v[4:5], 0, s[8:9]
	v_add_u32_e32 v10, s0, v10
	v_add_u32_e32 v10, s0, v10
	v_cmp_lt_i32_e64 s[0:1], s16, v10
	v_lshl_add_u64 v[6:7], v[6:7], 0, s[10:11]
	v_lshl_add_u64 v[6:7], v[6:7], 0, s[10:11]
	s_or_b64 s[14:15], s[0:1], s[14:15]
	v_lshl_add_u64 v[8:9], v[8:9], 0, s[12:13]
	v_lshl_add_u64 v[8:9], v[8:9], 0, s[12:13]
	s_andn2_b64 exec, exec, s[14:15]
	s_cbranch_execz .LBB0_206
.LBB0_204:
	global_load_dwordx4 v[18:21], v[8:9], off offset:-3072
	global_load_dwordx4 v[22:25], v[8:9], off offset:-2048
	global_load_dwordx4 v[26:29], v[8:9], off offset:-1024
	global_load_dwordx4 v[30:33], v[8:9], off
	v_lshl_add_u64 v[34:35], v[8:9], 0, s[12:13]
	v_lshl_add_u64 v[52:53], v[6:7], 0, s[10:11]
	v_lshl_add_u64 v[54:55], v[4:5], 0, s[8:9]
	global_load_dwordx4 v[36:39], v[34:35], off offset:-3072
	global_load_dwordx4 v[40:43], v[34:35], off offset:-2048
	global_load_dwordx4 v[44:47], v[34:35], off offset:-1024
	global_load_dwordx4 v[48:51], v[34:35], off
	s_waitcnt vmcnt(4)
	v_mul_f32_e32 v0, v19, v19
	s_waitcnt lgkmcnt(0)
	v_mul_f32_e32 v2, v23, v23
	v_mul_f32_e32 v3, v27, v27
	v_fmac_f32_e32 v0, v18, v18
	v_fmac_f32_e32 v2, v22, v22
	v_mul_f32_e32 v17, v31, v31
	v_fmac_f32_e32 v3, v26, v26
	v_fmac_f32_e32 v0, v20, v20
	v_fmac_f32_e32 v2, v24, v24
	v_fmac_f32_e32 v17, v30, v30
	v_fmac_f32_e32 v3, v28, v28
	v_fmac_f32_e32 v0, v21, v21
	v_fmac_f32_e32 v2, v25, v25
	v_fmac_f32_e32 v17, v32, v32
	v_fmac_f32_e32 v3, v29, v29
	v_add_f32_e32 v0, v0, v2
	v_fmac_f32_e32 v17, v33, v33
	v_add_f32_e32 v0, v0, v3
	v_add_f32_e32 v0, v0, v17
	ds_bpermute_b32 v2, v11, v0
	v_cvt_pk_bf16_f32 v3, v20, v21
	v_cvt_pk_bf16_f32 v20, v26, v27
	v_cvt_pk_bf16_f32 v21, v28, v29
	s_waitcnt lgkmcnt(0)
	v_add_f32_e32 v0, v0, v2
	ds_bpermute_b32 v2, v12, v0
	s_waitcnt lgkmcnt(0)
	v_add_f32_e32 v0, v0, v2
	ds_bpermute_b32 v2, v13, v0
	s_waitcnt lgkmcnt(0)
	v_add_f32_e32 v0, v0, v2
	ds_bpermute_b32 v17, v14, v0
	v_cvt_pk_bf16_f32 v2, v18, v19
	v_cvt_pk_bf16_f32 v18, v22, v23
	v_cvt_pk_bf16_f32 v19, v24, v25
	global_store_dwordx2 v[6:7], v[2:3], off offset:-1024
	global_store_dwordx2 v[6:7], v[18:19], off offset:-512
	s_waitcnt lgkmcnt(0)
	v_add_f32_e32 v0, v0, v17
	ds_bpermute_b32 v17, v15, v0
	v_cvt_pk_bf16_f32 v18, v30, v31
	v_cvt_pk_bf16_f32 v19, v32, v33
	global_store_dwordx2 v[6:7], v[20:21], off
	global_store_dwordx2 v[6:7], v[18:19], off offset:512
	s_waitcnt lgkmcnt(0)
	v_add_f32_e32 v0, v0, v17
	ds_bpermute_b32 v2, v16, v0
	s_and_saveexec_b64 s[0:1], vcc
	s_cbranch_execz .Lprep_a
	s_waitcnt lgkmcnt(0)
	v_add_f32_e32 v0, v0, v2
	v_mov_b32_e32 v2, v1
	v_mov_b32_e32 v3, v1
	global_store_dwordx4 v[4:5], v[0:3], off
.Lprep_a:
	s_or_b64 exec, exec, s[0:1]
	s_waitcnt vmcnt(4)
	v_mul_f32_e32 v0, v37, v37
	s_waitcnt lgkmcnt(0)
	v_mul_f32_e32 v2, v41, v41
	v_mul_f32_e32 v3, v45, v45
	v_fmac_f32_e32 v0, v36, v36
	v_fmac_f32_e32 v2, v40, v40
	v_mul_f32_e32 v17, v49, v49
	v_fmac_f32_e32 v3, v44, v44
	v_fmac_f32_e32 v0, v38, v38
	v_fmac_f32_e32 v2, v42, v42
	v_fmac_f32_e32 v17, v48, v48
	v_fmac_f32_e32 v3, v46, v46
	v_fmac_f32_e32 v0, v39, v39
	v_fmac_f32_e32 v2, v43, v43
	v_fmac_f32_e32 v17, v50, v50
	v_fmac_f32_e32 v3, v47, v47
	v_add_f32_e32 v0, v0, v2
	v_fmac_f32_e32 v17, v51, v51
	v_add_f32_e32 v0, v0, v3
	v_add_f32_e32 v0, v0, v17
	ds_bpermute_b32 v2, v11, v0
	v_cvt_pk_bf16_f32 v3, v38, v39
	v_cvt_pk_bf16_f32 v38, v44, v45
	v_cvt_pk_bf16_f32 v39, v46, v47
	s_waitcnt lgkmcnt(0)
	v_add_f32_e32 v0, v0, v2
	ds_bpermute_b32 v2, v12, v0
	s_waitcnt lgkmcnt(0)
	v_add_f32_e32 v0, v0, v2
	ds_bpermute_b32 v2, v13, v0
	s_waitcnt lgkmcnt(0)
	v_add_f32_e32 v0, v0, v2
	ds_bpermute_b32 v17, v14, v0
	v_cvt_pk_bf16_f32 v2, v36, v37
	v_cvt_pk_bf16_f32 v36, v40, v41
	v_cvt_pk_bf16_f32 v37, v42, v43
	global_store_dwordx2 v[52:53], v[2:3], off offset:-1024
	global_store_dwordx2 v[52:53], v[36:37], off offset:-512
	s_waitcnt lgkmcnt(0)
	v_add_f32_e32 v0, v0, v17
	ds_bpermute_b32 v17, v15, v0
	v_cvt_pk_bf16_f32 v36, v48, v49
	v_cvt_pk_bf16_f32 v37, v50, v51
	global_store_dwordx2 v[52:53], v[38:39], off
	global_store_dwordx2 v[52:53], v[36:37], off offset:512
	s_waitcnt lgkmcnt(0)
	v_add_f32_e32 v0, v0, v17
	ds_bpermute_b32 v2, v16, v0
	s_and_saveexec_b64 s[0:1], vcc
	s_cbranch_execz .LBB0_203
	s_waitcnt lgkmcnt(0)
	v_add_f32_e32 v0, v0, v2
	v_mov_b32_e32 v2, v1
	v_mov_b32_e32 v3, v1
	global_store_dwordx4 v[54:55], v[0:3], off
	s_branch .LBB0_203

; DEVI int otid() { int t = threadIdx.x; asm volatile("" : "+v"(t)); return t; }
; DEVI int obid() { int t = blockIdx.x; asm volatile("" : "+s"(t)); return t; }
; DEVI void rms_final(float* io, const float* g) {
;     const int lane = otid() & 63, gw = obid() * 8 + (otid() >> 6), nw = gridDim.x * 8;
;     f32x4 gv[4];
; #pragma unroll
;     for (int i = 0; i < 4; ++i) gv[i] = *(const f32x4*)(g + i * 256 + lane * 4);
;     for (int r = gw; r < T_TOK; r += nw) {
;         float* s = io + (size_t)r * DM; f32x4 v[4]; float ss = 0.f;
; #pragma unroll
;         for (int i = 0; i < 4; ++i) { v[i] = *(const f32x4*)(s + i * 256 + lane * 4); ss += v[i][0] * v[i][0] + v[i][1] * v[i][1] + v[i][2] * v[i][2] + v[i][3] * v[i][3]; }
; #pragma unroll
;         for (int o = 32; o > 0; o >>= 1) ss += __shfl_xor(ss, o);
;         const float rs = rsqrtf(ss * (1.f / DM) + 1e-6f);
; #pragma unroll
;         for (int i = 0; i < 4; ++i) *(f32x4*)(s + i * 256 + lane * 4) = v[i] * rs * gv[i];
;     }
.LBB0_1818:
	global_load_dwordx4 v[26:29], v[16:17], off offset:-3072
	global_load_dwordx4 v[30:33], v[16:17], off offset:-2048
	global_load_dwordx4 v[34:37], v[16:17], off offset:-1024
	global_load_dwordx4 v[38:41], v[16:17], off
	v_lshl_add_u64 v[58:59], v[16:17], 0, s[2:3]
	global_load_dwordx4 v[60:63], v[58:59], off offset:-3072
	global_load_dwordx4 v[64:67], v[58:59], off offset:-2048
	global_load_dwordx4 v[68:71], v[58:59], off offset:-1024
	global_load_dwordx4 v[72:75], v[58:59], off
	v_add_u32_e32 v18, s20, v18
	v_add_u32_e32 v18, s20, v18
	v_cmp_lt_i32_e64 s[0:1], s7, v18
	s_or_b64 s[4:5], s[0:1], s[4:5]
	s_waitcnt vmcnt(7)
	v_mov_b32_e32 v44, v27
	s_waitcnt vmcnt(6)
	v_mov_b32_e32 v45, v31
	v_mov_b32_e32 v42, v26
	v_mov_b32_e32 v43, v30
	s_waitcnt vmcnt(5)
	v_mov_b32_e32 v52, v35
	s_waitcnt vmcnt(4)
	v_mov_b32_e32 v53, v39
	v_pk_mul_f32 v[44:45], v[44:45], v[44:45]
	v_mov_b32_e32 v46, v28
	v_mov_b32_e32 v47, v32
	v_mov_b32_e32 v50, v34
	v_mov_b32_e32 v51, v38
	v_pk_mul_f32 v[52:53], v[52:53], v[52:53]
	v_pk_fma_f32 v[42:43], v[42:43], v[42:43], v[44:45]
	v_mov_b32_e32 v48, v29
	v_mov_b32_e32 v49, v33
	v_mov_b32_e32 v54, v36
	v_mov_b32_e32 v55, v40
	v_pk_fma_f32 v[44:45], v[50:51], v[50:51], v[52:53]
	v_pk_fma_f32 v[42:43], v[46:47], v[46:47], v[42:43]
	v_mov_b32_e32 v56, v37
	v_mov_b32_e32 v57, v41
	v_pk_fma_f32 v[44:45], v[54:55], v[54:55], v[44:45]
	v_pk_fma_f32 v[42:43], v[48:49], v[48:49], v[42:43]
	v_pk_fma_f32 v[44:45], v[56:57], v[56:57], v[44:45]
	v_add_f32_e32 v42, v42, v43
	v_add_f32_e32 v42, v42, v44
	v_add_f32_e32 v42, v42, v45
	ds_bpermute_b32 v43, v19, v42
	s_waitcnt lgkmcnt(0)
	v_add_f32_e32 v42, v42, v43
	ds_bpermute_b32 v43, v20, v42
	s_waitcnt lgkmcnt(0)
	v_add_f32_e32 v42, v42, v43
	ds_bpermute_b32 v43, v21, v42
	s_waitcnt lgkmcnt(0)
	v_add_f32_e32 v42, v42, v43
	ds_bpermute_b32 v43, v22, v42
	s_waitcnt lgkmcnt(0)
	v_add_f32_e32 v42, v42, v43
	ds_bpermute_b32 v43, v23, v42
	s_waitcnt lgkmcnt(0)
	v_add_f32_e32 v42, v42, v43
	ds_bpermute_b32 v43, v24, v42
	s_waitcnt lgkmcnt(0)
	v_add_f32_e32 v42, v42, v43
	v_fmamk_f32 v42, v42, 0x3a800000, v25
	v_mul_f32_e32 v43, 0x4b800000, v42
	v_cmp_gt_f32_e32 vcc, s6, v42
	s_nop 1
	v_cndmask_b32_e32 v42, v42, v43, vcc
	v_rsq_f32_e32 v42, v42
	s_nop 0
	v_mul_f32_e32 v43, 0x45800000, v42
	v_cndmask_b32_e32 v42, v42, v43, vcc
	v_pk_mul_f32 v[26:27], v[26:27], v[42:43] op_sel_hi:[1,0]
	v_pk_mul_f32 v[28:29], v[28:29], v[42:43] op_sel_hi:[1,0]
	v_pk_mul_f32 v[30:31], v[30:31], v[42:43] op_sel_hi:[1,0]
	v_pk_mul_f32 v[32:33], v[32:33], v[42:43] op_sel_hi:[1,0]
	v_pk_mul_f32 v[34:35], v[34:35], v[42:43] op_sel_hi:[1,0]
	v_pk_mul_f32 v[36:37], v[36:37], v[42:43] op_sel_hi:[1,0]
	v_pk_mul_f32 v[38:39], v[38:39], v[42:43] op_sel_hi:[1,0]
	v_pk_mul_f32 v[40:41], v[40:41], v[42:43] op_sel_hi:[1,0]
	v_pk_mul_f32 v[28:29], v[2:3], v[28:29]
	v_pk_mul_f32 v[26:27], v[0:1], v[26:27]
	v_pk_mul_f32 v[32:33], v[6:7], v[32:33]
	v_pk_mul_f32 v[30:31], v[4:5], v[30:31]
	v_pk_mul_f32 v[36:37], v[10:11], v[36:37]
	v_pk_mul_f32 v[34:35], v[8:9], v[34:35]
	v_pk_mul_f32 v[40:41], v[14:15], v[40:41]
	v_pk_mul_f32 v[38:39], v[12:13], v[38:39]
	global_store_dwordx4 v[16:17], v[26:29], off offset:-3072
	global_store_dwordx4 v[16:17], v[30:33], off offset:-2048
	global_store_dwordx4 v[16:17], v[34:37], off offset:-1024
	global_store_dwordx4 v[16:17], v[38:41], off
	s_waitcnt vmcnt(7)
	v_mov_b32_e32 v44, v61
	s_waitcnt vmcnt(6)
	v_mov_b32_e32 v45, v65
	v_mov_b32_e32 v42, v60
	v_mov_b32_e32 v43, v64
	s_waitcnt vmcnt(5)
	v_mov_b32_e32 v52, v69
	s_waitcnt vmcnt(4)
	v_mov_b32_e32 v53, v73
	v_pk_mul_f32 v[44:45], v[44:45], v[44:45]
	v_mov_b32_e32 v46, v62
	v_mov_b32_e32 v47, v66
	v_mov_b32_e32 v50, v68
	v_mov_b32_e32 v51, v72
	v_pk_mul_f32 v[52:53], v[52:53], v[52:53]
	v_pk_fma_f32 v[42:43], v[42:43], v[42:43], v[44:45]
	v_mov_b32_e32 v48, v63
	v_mov_b32_e32 v49, v67
	v_mov_b32_e32 v54, v70
	v_mov_b32_e32 v55, v74
	v_pk_fma_f32 v[44:45], v[50:51], v[50:51], v[52:53]
	v_pk_fma_f32 v[42:43], v[46:47], v[46:47], v[42:43]
	v_mov_b32_e32 v56, v71
	v_mov_b32_e32 v57, v75
	v_pk_fma_f32 v[44:45], v[54:55], v[54:55], v[44:45]
	v_pk_fma_f32 v[42:43], v[48:49], v[48:49], v[42:43]
	v_pk_fma_f32 v[44:45], v[56:57], v[56:57], v[44:45]
	v_add_f32_e32 v42, v42, v43
	v_add_f32_e32 v42, v42, v44
	v_add_f32_e32 v42, v42, v45
	ds_bpermute_b32 v43, v19, v42
	s_waitcnt lgkmcnt(0)
	v_add_f32_e32 v42, v42, v43
	ds_bpermute_b32 v43, v20, v42
	s_waitcnt lgkmcnt(0)
	v_add_f32_e32 v42, v42, v43
	ds_bpermute_b32 v43, v21, v42
	s_waitcnt lgkmcnt(0)
	v_add_f32_e32 v42, v42, v43
	ds_bpermute_b32 v43, v22, v42
	s_waitcnt lgkmcnt(0)
	v_add_f32_e32 v42, v42, v43
	ds_bpermute_b32 v43, v23, v42
	s_waitcnt lgkmcnt(0)
	v_add_f32_e32 v42, v42, v43
	ds_bpermute_b32 v43, v24, v42
	s_waitcnt lgkmcnt(0)
	v_add_f32_e32 v42, v42, v43
	v_fmamk_f32 v42, v42, 0x3a800000, v25
	v_mul_f32_e32 v43, 0x4b800000, v42
	v_cmp_gt_f32_e32 vcc, s6, v42
	s_nop 1
	v_cndmask_b32_e32 v42, v42, v43, vcc
	v_rsq_f32_e32 v42, v42
	s_nop 0
	v_mul_f32_e32 v43, 0x45800000, v42
	v_cndmask_b32_e32 v42, v42, v43, vcc
	v_pk_mul_f32 v[60:61], v[60:61], v[42:43] op_sel_hi:[1,0]
	v_pk_mul_f32 v[62:63], v[62:63], v[42:43] op_sel_hi:[1,0]
	v_pk_mul_f32 v[64:65], v[64:65], v[42:43] op_sel_hi:[1,0]
	v_pk_mul_f32 v[66:67], v[66:67], v[42:43] op_sel_hi:[1,0]
	v_pk_mul_f32 v[68:69], v[68:69], v[42:43] op_sel_hi:[1,0]
	v_pk_mul_f32 v[70:71], v[70:71], v[42:43] op_sel_hi:[1,0]
	v_pk_mul_f32 v[72:73], v[72:73], v[42:43] op_sel_hi:[1,0]
	v_pk_mul_f32 v[74:75], v[74:75], v[42:43] op_sel_hi:[1,0]
	v_pk_mul_f32 v[62:63], v[2:3], v[62:63]
	v_pk_mul_f32 v[60:61], v[0:1], v[60:61]
	v_pk_mul_f32 v[66:67], v[6:7], v[66:67]
	v_pk_mul_f32 v[64:65], v[4:5], v[64:65]
	v_pk_mul_f32 v[70:71], v[10:11], v[70:71]
	v_pk_mul_f32 v[68:69], v[8:9], v[68:69]
	v_pk_mul_f32 v[74:75], v[14:15], v[74:75]
	v_pk_mul_f32 v[72:73], v[12:13], v[72:73]
	global_store_dwordx4 v[58:59], v[60:63], off offset:-3072
	global_store_dwordx4 v[58:59], v[64:67], off offset:-2048
	global_store_dwordx4 v[58:59], v[68:71], off offset:-1024
	global_store_dwordx4 v[58:59], v[72:75], off
	v_lshl_add_u64 v[16:17], v[16:17], 0, s[2:3]
	v_lshl_add_u64 v[16:17], v[16:17], 0, s[2:3]
	s_andn2_b64 exec, exec, s[4:5]
	s_cbranch_execnz .LBB0_1818
